# weight-prep split v3: phase 0 of every layer converts only the in-projection weights (items <2128); workgroups 128-255 do all other weight prep in their idle slot after phase 1, layer 0 included
# baseline (speedup 1.0000x reference)
; __global__ void __launch_bounds__(512, 2) mk_fwd(Args args) {
;     ...
;     for (int ph = args.ph_lo; ph < args.ph_hi; ++ph) {
;         if (ph == args.ph_lo + 1) cg::this_grid().sync();
;         else if (ph > args.ph_lo) xcd_barrier(bar);
;         const int l = ph / PH_PER_LAYER; int p = 0, rep = ph % PH_PER_LAYER, nrep = 1;
;         for (; p < NPH; ++p) { nrep = 1 + ((REP_MASK >> p) & 1); if (rep < nrep) break; rep -= nrep; }
.LBB0_9:
	v_readlane_b32 s0, v255, 12
	s_cmp_eq_u32 s0, 1
	s_cbranch_scc1 .Lwp_done
	s_cmp_ge_i32 s34, 36
	s_cbranch_scc1 .Lwp_adv
	s_mul_hi_i32 s0, s34, 0x38e38e39
	s_lshr_b32 s1, s0, 31
	s_ashr_i32 s0, s0, 1
	s_add_i32 s0, s0, s1
	s_mul_i32 s0, s0, 9
	s_sub_i32 s0, s34, s0
	s_cmp_lg_u32 s0, 1
	s_cbranch_scc1 .Lwp_adv
	s_cmpk_lt_i32 s62, 0x80
	s_cbranch_scc1 .Lwp_adv
	v_readlane_b32 s0, v253, 49
	v_readlane_b32 s1, v253, 50
	s_nop 4
	s_load_dword s0, s[0:1], 0x0
	s_waitcnt lgkmcnt(0)
	s_cmpk_lg_i32 s0, 0x100
	s_cbranch_scc1 .Lwp_adv
	s_mov_b32 s0, 1
	v_writelane_b32 v255, s0, 12
	s_sub_i32 s34, s34, 1
	s_waitcnt vmcnt(0) lgkmcnt(0)
	s_barrier
	s_branch .LBB0_75

; #define LAS __attribute__((address_space(3)))
; __device__ __forceinline__ void wprep_phase(const WArgs& a, LAS float* scr, int gw, int NGW, int lane, int gtid, int NGT) {
;     constexpr int I0 = 16 * 133, I1 = 6 * 24, I2 = 4 * 32, I3 = 8 * 32, I4 = 4 * 32, I5 = 16 * 32, I6 = 16 * 128, I7 = 64 * 32;
;     constexpr int NIT = I0 + I1 + I2 + I3 + I4 + I5 + I6 + I7;
;     for (int it = gw; it < NIT; it += NGW) {
.LBB0_567:
	s_andn2_b64 vcc, exec, s[0:1]
	s_cbranch_vccnz .LBB0_797
	s_add_u32 s24, s50, 0x200000
	s_addc_u32 s25, s51, 0
	s_cmp_lg_u32 s18, 1
	s_mov_b64 s[0:1], -1
	s_cbranch_scc0 .LBB0_729
	v_mov_b32_e32 v81, v222
	s_lshl_b32 s55, s2, 3
	v_readfirstlane_b32 s0, v81
	s_ashr_i32 s54, s0, 6
	s_lshl_b32 s30, s76, 8
	s_mov_b32 s96, s34
	s_add_i32 s34, s54, s55
	v_readlane_b32 s0, v255, 12
	s_cmp_eq_u32 s0, 1
	s_cbranch_scc1 .Lwp_e1
	s_mov_b32 s0, 0
	s_cmpk_lg_i32 s35, 0x100
	s_cbranch_scc1 .Lwp_e0
	s_mov_b32 s0, 2

; #define LAS __attribute__((address_space(3)))
; __device__ __forceinline__ void wprep_phase(const WArgs& a, LAS float* scr, int gw, int NGW, int lane, int gtid, int NGT) {
;     constexpr int I0 = 16 * 133, I1 = 6 * 24, I2 = 4 * 32, I3 = 8 * 32, I4 = 4 * 32, I5 = 16 * 32, I6 = 16 * 128, I7 = 64 * 32;
;     constexpr int NIT = I0 + I1 + I2 + I3 + I4 + I5 + I6 + I7;
;     for (int it = gw; it < NIT; it += NGW) {
;         int r = it;
;         if (r < I0) { const int kb = r / 133, nb = r % 133; tr_item(a.w_in, IN_COLS, 64 * kb, 32 * nb, a.W + WO_IN, 1024, win_dst(32 * nb), scr, lane, a.g_mix); continue; } r -= I0;
.Lwp_e1:
	s_ashr_i32 s77, s76, 31
	s_ashr_i32 s31, s30, 31
	s_cmpk_gt_i32 s34, 0x1cdf
	v_and_b32_e32 v80, 63, v81
	s_cbranch_scc1 .LBB0_698
	s_lshl_b32 s0, s76, 10
	s_ashr_i32 s1, s0, 31
	s_mov_b64 s[4:5], s[80:81]
	v_readlane_b32 s80, v253, 0
	s_lshl_b64 s[0:1], s[0:1], 2
	v_readlane_b32 s81, v253, 1
	v_readlane_b32 s82, v253, 2
	v_readlane_b32 s83, v253, 3
	s_mov_b64 s[80:81], s[4:5]
	s_add_u32 s36, s82, s0
	v_readlane_b32 s4, v253, 32
	s_addc_u32 s37, s83, s1
	v_readlane_b32 s14, v253, 42
	v_readlane_b32 s15, v253, 43
	s_add_u32 s40, s14, s0
	s_mul_i32 s0, s76, 0x180
	s_addc_u32 s41, s15, s1
	s_ashr_i32 s1, s0, 31
	v_readlane_b32 s92, v253, 12
	s_lshl_b64 s[0:1], s[0:1], 2
	v_readlane_b32 s93, v253, 13
	v_readlane_b32 s5, v253, 33
	s_add_u32 s42, s92, s0
	s_addc_u32 s43, s93, s1
	s_lshl_b64 s[0:1], s[30:31], 2
	s_mov_b64 s[4:5], s[76:77]
	v_readlane_b32 s64, v253, 16
	v_readlane_b32 s65, v253, 17
	s_add_u32 s52, s64, s0
	v_readlane_b32 s18, v253, 46
	v_readlane_b32 s76, v253, 28
	v_readlane_b32 s77, v253, 29
	s_addc_u32 s53, s65, s1
	s_lshl_b64 s[0:1], s[4:5], 24
	v_readlane_b32 s19, v253, 47
	s_mov_b64 s[76:77], s[4:5]
	s_add_u32 s4, s18, s0
	v_readlane_b32 s16, v253, 44
	s_addc_u32 s5, s19, s1
	v_readlane_b32 s17, v253, 45
	s_add_u32 s0, s16, s0
	v_readlane_b32 s12, v253, 40
	s_addc_u32 s1, s17, s1
	s_lshl_b64 s[20:21], s[76:77], 22
	v_readlane_b32 s13, v253, 41
	s_add_u32 s20, s12, s20
	v_readlane_b32 s8, v253, 36
	s_addc_u32 s21, s13, s21
	s_lshl_b64 s[38:39], s[76:77], 20
	v_readlane_b32 s9, v253, 37
	s_add_u32 s44, s8, s38
	v_readlane_b32 s68, v253, 20
	s_addc_u32 s45, s9, s39
	s_lshl_b64 s[46:47], s[76:77], 21
	v_readlane_b32 s69, v253, 21
	s_add_u32 s46, s68, s46
	v_readlane_b32 s66, v253, 18
	s_addc_u32 s47, s69, s47
	v_lshlrev_b32_e32 v0, 4, v80
	v_readlane_b32 s67, v253, 19
	s_add_u32 s38, s66, s38
	v_and_b32_e32 v0, 0x70, v0
	v_readlane_b32 s94, v253, 14
	s_addc_u32 s39, s67, s39
	s_waitcnt vmcnt(0) lgkmcnt(0)
	v_lshl_add_u64 v[40:41], s[0:1], 0, v[0:1]
	s_mul_i32 s0, s76, 0x120000
	v_readlane_b32 s95, v253, 15
	s_mul_hi_i32 s15, s76, 0x120000
	s_add_u32 s0, s94, s0
	v_readlane_b32 s84, v253, 4
	s_addc_u32 s1, s95, s15
	s_mul_i32 s16, s76, 0x10a0000
	v_readlane_b32 s85, v253, 5
	s_mul_hi_i32 s15, s76, 0x10a0000
	s_add_u32 s16, s84, s16
	v_lshlrev_b32_e32 v2, 3, v80
	s_addc_u32 s17, s85, s15
	s_lshl_b32 s15, s54, 14
	v_lshrrev_b32_e32 v44, 3, v80
	v_and_b32_e32 v2, 56, v2
	s_add_i32 s15, s15, 0
	v_mul_u32_u24_e32 v3, 0x84, v2
	v_lshlrev_b32_e32 v4, 2, v44
	v_lshl_add_u64 v[38:39], s[4:5], 0, v[0:1]
	v_lshl_add_u64 v[42:43], s[20:21], 0, v[0:1]
	v_add_u32_e32 v82, s15, v0
	v_add3_u32 v87, s15, v3, v4
	v_or_b32_e32 v3, 32, v44
	v_lshl_add_u64 v[46:47], s[44:45], 0, v[0:1]
	v_lshl_add_u64 v[48:49], s[46:47], 0, v[0:1]
	v_lshl_add_u64 v[50:51], s[38:39], 0, v[0:1]
	v_lshl_add_u64 v[52:53], s[0:1], 0, v[0:1]
	v_lshl_add_u64 v[54:55], s[16:17], 0, v[0:1]
	v_lshlrev_b32_e32 v0, 1, v2
	v_mul_u32_u24_e32 v88, 0x84, v3
	v_lshl_add_u64 v[2:3], s[50:51], 0, v[0:1]
	s_mov_b64 s[0:1], 0x17d0000
	v_lshl_add_u64 v[58:59], v[2:3], 0, s[0:1]
	s_mov_b64 s[0:1], 0xfd0000
	v_lshl_add_u64 v[60:61], v[2:3], 0, s[0:1]
	s_mov_b64 s[0:1], 0xdd0000
	v_lshl_add_u64 v[62:63], v[2:3], 0, s[0:1]
	s_mov_b64 s[0:1], 0xbd0600
	v_lshl_add_u64 v[64:65], v[2:3], 0, s[0:1]
	s_mov_b64 s[0:1], 0xbd0200
	v_lshl_add_u64 v[66:67], v[2:3], 0, s[0:1]
	s_mov_b64 s[0:1], 0xb50000
	v_readlane_b32 s78, v253, 30
	v_readlane_b32 s79, v253, 31
	v_lshl_add_u64 v[68:69], v[2:3], 0, s[0:1]
	s_mov_b64 s[0:1], 0xb10000
	v_readlane_b32 s70, v253, 22
	v_readlane_b32 s71, v253, 23
	v_readlane_b32 s73, v253, 25
	v_readlane_b32 s75, v253, 27
	v_readlane_b32 s78, v254, 58
	v_readlane_b32 s94, v255, 0
	v_lshl_add_u64 v[70:71], v[2:3], 0, s[0:1]
	s_mov_b64 s[0:1], 0xa80000
	s_movk_i32 s83, 0x600
	s_mov_b32 s71, 0x30000
	s_movk_i32 s75, 0x5000
	s_movk_i32 s73, 0x60
	s_movk_i32 s70, 0x6000
	v_readlane_b32 s79, v254, 59
	s_movk_i32 s64, 0x2000
	s_movk_i32 s65, 0xd0
	s_mov_b32 s63, 0x2aaaaaab
	s_movk_i32 s66, 0x4000
	v_mul_u32_u24_e32 v83, 0x84, v44
	v_or_b32_e32 v84, 8, v44
	v_or_b32_e32 v85, 16, v44
	v_or_b32_e32 v86, 24, v44
	v_lshl_add_u64 v[56:57], s[24:25], 0, v[0:1]
	v_lshl_add_u64 v[72:73], v[2:3], 0, s[0:1]
	v_mov_b32_e32 v45, v1
	v_readlane_b32 s0, v255, 12
	s_cmp_eq_u32 s0, 1
	s_cbranch_scc0 .Lwp_norm
	s_add_i32 s34, s34, 0x450
	s_lshr_b32 s94, s94, 1

; __device__ __forceinline__ void wprep_phase(const WArgs& a, LAS float* scr, int gw, int NGW, int lane, int gtid, int NGT) {
;     ...
;     for (int it = gw; it < NIT; it += NGW) {
;         int r = it;
.LBB0_573:
	s_add_i32 s46, s46, s94
	s_add_i32 s15, s15, s16
	s_add_i32 s17, s17, s19
	s_add_i32 s44, s44, s45
	s_cmpk_gt_i32 s46, 0x1cdf
	s_cbranch_scc1 .LBB0_698
	s_cmpk_lt_i32 s46, 0x850
	s_cbranch_scc1 .LBB0_574
	v_readlane_b32 s0, v255, 12
	s_cmp_eq_u32 s0, 2
	s_cbranch_scc1 .LBB0_698

; __device__ __forceinline__ void wprep_phase(const WArgs& a, LAS float* scr, int gw, int NGW, int lane, int gtid, int NGT) {
;     ...
;     for (int e = gtid; e < 256; e += NGT) a.cdec[e] = -8.0f * log1pf(expf(-a.lam[e]));
.LBB0_698:
	v_readlane_b32 s0, v255, 12
	s_cmp_eq_u32 s0, 1
	s_cbranch_scc0 .Lwp_x
	s_sub_i32 s34, s34, 0x450

; __global__ void __launch_bounds__(512, 2) mk_fwd(Args args) {
;     ...
;             if (l == 0) { for (int e = gtid; e < SEQ * 16; e += NGT) { const int pos = e >> 4, i = e & 15; const float inv = powf(10000.0f, -(float)(2 * i) / 32.0f); const float ang = (float)pos * inv; cs[e] = cosf(ang); sn[e] = sinf(ang); } }
;             if (l == 0) xinit_phase(args.in[0], X, Hb, ssq1, gw, NGW, lane);
.LBB0_711:
	s_or_b64 exec, exec, s[20:21]
	v_readlane_b32 s0, v255, 12
	s_cmp_eq_u32 s0, 1
	s_cbranch_scc1 .LBB0_728
	v_lshl_add_u32 v2, s2, 9, v81
	s_add_i32 s0, s96, 8
	s_cmp_gt_u32 s0, 16
	s_cbranch_scc1 .LBB0_728
	s_mov_b32 s0, 0x10000
	v_cmp_gt_i32_e32 vcc, s0, v2
	s_and_saveexec_b64 s[20:21], vcc
	s_cbranch_execz .LBB0_723
	v_ashrrev_i32_e32 v3, 31, v2
	s_ashr_i32 s37, s36, 31
	v_lshlrev_b32_e32 v0, 1, v81
	v_lshl_add_u64 v[4:5], v[2:3], 2, s[58:59]
	s_lshl_b64 s[30:31], s[36:37], 2
	v_lshl_add_u32 v3, s2, 10, v0
	s_lshl_b32 s15, s35, 10
	s_mov_b64 s[50:51], 0
	s_branch .LBB0_715
